# strategy 7: 108 pairs of v_mul_f32 in the up GEMM epilogue fused into v_pk_mul_f32 (on top of v58)
# baseline (speedup 1.0000x reference)
;     __device__ __forceinline__ void operator()(f32x4 (&acc)[2][2][4][2], const Unit& u, int wr, int wc, int fr_in, int fq_in, int wid, LAS unsigned char* lds) const {
;     ...
;         float sv[8]; u32x4 cv[4];
; #pragma unroll
;         for (int k = 0; k < 8; ++k) sv[k] = sa[rowg + (k >> 2) * HALF + (k & 3) * 16 + fr] * (1.0f / 127.0f);
; #pragma unroll
;         for (int k = 0; k < 4; ++k) cv[k] = *(const u32x4*)(cmax + colw + 8 * fq + (k >> 1) * CBJ + (k & 1) * 4);
; #pragma unroll
;         for (int ai = 0; ai < 2; ++ai)
; #pragma unroll
;             for (int m = 0; m < 4; ++m) {
;                 const float s = sv[ai * 4 + m];
;                 float mx = 0.f;
; #pragma unroll
;                 for (int bj = 0; bj < 2; ++bj) {
;                     const v4i_t i0 = __builtin_bit_cast(v4i_t, acc[ai][bj][m][0]), i1 = __builtin_bit_cast(v4i_t, acc[ai][bj][m][1]);
;                     const u32x4 c0_ = cv[bj * 2], c1_ = cv[bj * 2 + 1];
;                     f32x4 v0, v1;
; #pragma unroll
;                     for (int j = 0; j < 4; ++j) { const float a = fmaxf((float)i0[j] * (s * __uint_as_float(c0_[j])), 0.f), b = fmaxf((float)i1[j] * (s * __uint_as_float(c1_[j])), 0.f); v0[j] = a * a; v1[j] = b * b; mx = fmaxf(mx, fmaxf(v0[j], v1[j])); }
.LBB0_1339:
	s_mov_b32 s0, s81
	s_mov_b32 s1, -1
	s_lshl_b32 s40, s52, 8
	v_mov_b32_e32 v130, v162
	v_mov_b32_e32 v166, v163
	s_add_i32 s0, s40, s47
	v_readlane_b32 s42, v249, 57
	v_add_u32_e32 v114, s0, v130
	v_ashrrev_i32_e32 v115, 31, v114
	v_readlane_b32 s43, v249, 58
	s_lshl_b32 s1, s53, 8
	s_or_b32 s82, s1, s84
	v_lshl_add_u64 v[116:117], v[114:115], 2, s[42:43]
	global_load_dword v115, v[116:117], off
	v_add_u32_e32 v116, 16, v114
	v_ashrrev_i32_e32 v117, 31, v116
	v_lshl_add_u64 v[116:117], v[116:117], 2, s[42:43]
	global_load_dword v176, v[116:117], off
	v_add_u32_e32 v116, 32, v114
	v_ashrrev_i32_e32 v117, 31, v116
	v_lshl_add_u64 v[116:117], v[116:117], 2, s[42:43]
	global_load_dword v175, v[116:117], off
	v_add_u32_e32 v116, 48, v114
	v_ashrrev_i32_e32 v117, 31, v116
	v_lshl_add_u64 v[116:117], v[116:117], 2, s[42:43]
	global_load_dword v174, v[116:117], off
	v_add_u32_e32 v116, 0x80, v114
	v_ashrrev_i32_e32 v117, 31, v116
	v_lshl_add_u64 v[116:117], v[116:117], 2, s[42:43]
	global_load_dword v173, v[116:117], off
	v_add_u32_e32 v116, 0x90, v114
	v_ashrrev_i32_e32 v117, 31, v116
	v_lshl_add_u64 v[116:117], v[116:117], 2, s[42:43]
	global_load_dword v172, v[116:117], off
	v_add_u32_e32 v116, 0xa0, v114
	v_add_u32_e32 v114, 0xb0, v114
	v_ashrrev_i32_e32 v117, 31, v116
	s_ashr_i32 s83, s82, 31
	v_lshl_add_u64 v[116:117], v[116:117], 2, s[42:43]
	v_lshlrev_b32_e32 v160, 3, v166
	v_ashrrev_i32_e32 v161, 31, v160
	global_load_dword v171, v[116:117], off
	v_mov_b32_e32 v182, v114
	v_ashrrev_i32_e32 v183, 31, v114
	v_lshl_add_u64 v[182:183], v[182:183], 2, s[42:43]
	global_load_dword v167, v[182:183], off
	s_lshl_b64 s[98:99], s[82:83], 2
	s_add_u32 s98, s35, s98
	s_addc_u32 s99, s38, s99
	v_lshl_add_u64 v[184:185], v[160:161], 2, s[98:99]
	global_load_dwordx4 v[126:129], v[184:185], off offset:16
	global_load_dwordx4 v[136:139], v[184:185], off
	global_load_dwordx4 v[186:189], v[184:185], off offset:144
	global_load_dwordx4 v[190:193], v[184:185], off offset:128
	v_cvt_f32_i32_e32 v144, v144
	v_cvt_f32_i32_e32 v145, v145
	v_cvt_f32_i32_e32 v140, v140
	v_cvt_f32_i32_e32 v141, v141
	v_cvt_f32_i32_e32 v146, v146
	v_cvt_f32_i32_e32 v147, v147
	v_cvt_f32_i32_e32 v142, v142
	v_cvt_f32_i32_e32 v143, v143
	v_cvt_f32_i32_e32 v132, v132
	v_cvt_f32_i32_e32 v133, v133
	v_cvt_f32_i32_e32 v122, v122
	v_cvt_f32_i32_e32 v123, v123
	v_cvt_f32_i32_e32 v134, v134
	v_cvt_f32_i32_e32 v124, v124
	v_cvt_f32_i32_e32 v135, v135
	v_cvt_f32_i32_e32 v125, v125
	v_and_b32_e32 v169, 64, v204
	v_xor_b32_e32 v168, 16, v204
	v_add_u32_e32 v170, 64, v169
	v_cmp_lt_i32_e32 vcc, v168, v170
	v_cvt_f32_i32_e32 v110, v110
	v_cvt_f32_i32_e32 v111, v111
	v_cvt_f32_i32_e32 v106, v106
	v_cvt_f32_i32_e32 v107, v107
	v_cvt_f32_i32_e32 v112, v112
	v_cvt_f32_i32_e32 v113, v113
	v_cvt_f32_i32_e32 v108, v108
	v_cvt_f32_i32_e32 v109, v109
	v_cvt_f32_i32_e32 v102, v102
	v_cvt_f32_i32_e32 v103, v103
	v_cvt_f32_i32_e32 v98, v98
	v_cvt_f32_i32_e32 v99, v99
	v_cvt_f32_i32_e32 v104, v104
	v_cvt_f32_i32_e32 v100, v100
	v_cvt_f32_i32_e32 v105, v105
	v_cvt_f32_i32_e32 v101, v101
	v_cvt_f32_i32_e32 v94, v94
	v_cvt_f32_i32_e32 v95, v95
	v_cvt_f32_i32_e32 v90, v90
	v_cvt_f32_i32_e32 v91, v91
	v_cvt_f32_i32_e32 v96, v96
	v_cvt_f32_i32_e32 v97, v97
	v_cvt_f32_i32_e32 v92, v92
	v_cvt_f32_i32_e32 v93, v93
	v_cvt_f32_i32_e32 v86, v86
	v_cvt_f32_i32_e32 v87, v87
	v_cvt_f32_i32_e32 v82, v82
	v_cvt_f32_i32_e32 v83, v83
	v_cvt_f32_i32_e32 v88, v88
	v_cvt_f32_i32_e32 v84, v84
	v_cvt_f32_i32_e32 v89, v89
	v_cvt_f32_i32_e32 v85, v85
	v_cvt_f32_i32_e32 v78, v78
	v_cvt_f32_i32_e32 v79, v79
	v_cvt_f32_i32_e32 v74, v74
	v_cvt_f32_i32_e32 v75, v75
	v_cvt_f32_i32_e32 v80, v80
	v_cvt_f32_i32_e32 v81, v81
	v_cvt_f32_i32_e32 v76, v76
	v_cvt_f32_i32_e32 v77, v77
	v_cvt_f32_i32_e32 v70, v70
	v_cvt_f32_i32_e32 v71, v71
	v_cvt_f32_i32_e32 v66, v66
	v_cvt_f32_i32_e32 v67, v67
	v_cvt_f32_i32_e32 v72, v72
	v_cvt_f32_i32_e32 v68, v68
	v_cvt_f32_i32_e32 v73, v73
	v_cvt_f32_i32_e32 v69, v69
	v_cvt_f32_i32_e32 v62, v62
	v_cvt_f32_i32_e32 v63, v63
	v_cvt_f32_i32_e32 v58, v58
	v_cvt_f32_i32_e32 v59, v59
	v_cvt_f32_i32_e32 v64, v64
	v_cvt_f32_i32_e32 v65, v65
	v_cvt_f32_i32_e32 v60, v60
	v_cvt_f32_i32_e32 v61, v61
	v_cvt_f32_i32_e32 v54, v54
	v_cvt_f32_i32_e32 v55, v55
	v_cvt_f32_i32_e32 v50, v50
	v_cvt_f32_i32_e32 v51, v51
	v_cvt_f32_i32_e32 v56, v56
	v_cvt_f32_i32_e32 v52, v52
	v_cvt_f32_i32_e32 v57, v57
	v_cvt_f32_i32_e32 v53, v53
	v_cvt_f32_i32_e32 v46, v46
	v_cvt_f32_i32_e32 v47, v47
	v_cvt_f32_i32_e32 v42, v42
	v_cvt_f32_i32_e32 v43, v43
	v_cvt_f32_i32_e32 v48, v48
	v_cvt_f32_i32_e32 v49, v49
	v_cvt_f32_i32_e32 v44, v44
	v_cvt_f32_i32_e32 v45, v45
	v_cvt_f32_i32_e32 v38, v38
	v_cvt_f32_i32_e32 v39, v39
	v_cvt_f32_i32_e32 v34, v34
	v_cvt_f32_i32_e32 v35, v35
	v_cvt_f32_i32_e32 v40, v40
	v_cvt_f32_i32_e32 v36, v36
	v_cvt_f32_i32_e32 v41, v41
	v_cvt_f32_i32_e32 v37, v37
	v_cvt_f32_i32_e32 v30, v30
	v_cvt_f32_i32_e32 v31, v31
	v_cvt_f32_i32_e32 v26, v26
	v_cvt_f32_i32_e32 v27, v27
	v_cvt_f32_i32_e32 v32, v32
	v_cvt_f32_i32_e32 v33, v33
	v_cvt_f32_i32_e32 v28, v28
	v_cvt_f32_i32_e32 v29, v29
	v_cvt_f32_i32_e32 v22, v22
	v_cvt_f32_i32_e32 v18, v18
	v_cvt_f32_i32_e32 v19, v19
	v_cvt_f32_i32_e32 v20, v20
	v_cvt_f32_i32_e32 v21, v21
	v_cvt_f32_i32_e32 v14, v14
	v_cvt_f32_i32_e32 v10, v10
	v_cvt_f32_i32_e32 v11, v11
	v_cvt_f32_i32_e32 v12, v12
	v_cvt_f32_i32_e32 v13, v13
	v_cvt_f32_i32_e32 v6, v6
	v_cvt_f32_i32_e32 v2, v2
	v_cvt_f32_i32_e32 v3, v3
	v_cvt_f32_i32_e32 v4, v4
	v_cvt_f32_i32_e32 v5, v5
	s_waitcnt vmcnt(5)
;     __device__ __forceinline__ void operator()(f32x4 (&acc)[2][2][4][2], const Unit& u, int wr, int wc, int fr_in, int fq_in, int wid, LAS unsigned char* lds) const {
;     ...
;         for (int ai = 0; ai < 2; ++ai)
; #pragma unroll
;             for (int m = 0; m < 4; ++m) {
;                 const float s = sv[ai * 4 + m];
;                 float mx = 0.f;
; #pragma unroll
;                 for (int bj = 0; bj < 2; ++bj) {
;                     const v4i_t i0 = __builtin_bit_cast(v4i_t, acc[ai][bj][m][0]), i1 = __builtin_bit_cast(v4i_t, acc[ai][bj][m][1]);
;                     const u32x4 c0_ = cv[bj * 2], c1_ = cv[bj * 2 + 1];
;                     f32x4 v0, v1;
; #pragma unroll
;                     for (int j = 0; j < 4; ++j) { const float a = fmaxf((float)i0[j] * (s * __uint_as_float(c0_[j])), 0.f), b = fmaxf((float)i1[j] * (s * __uint_as_float(c1_[j])), 0.f); v0[j] = a * a; v1[j] = b * b; mx = fmaxf(mx, fmaxf(v0[j], v1[j])); }
;                     acc[ai][bj][m][0] = v0; acc[ai][bj][m][1] = v1;
;                 }
;                 mx = fmaxf(mx, __shfl_xor(mx, 16)); mx = fmaxf(mx, __shfl_xor(mx, 32));
;                 if (fq == 0) lmx[wc * 256 + wr * 64 + ai * HALF + m * 16 + fr] = mx;
	v_mul_f32_e32 v177, 0x3c010204, v115
	v_ashrrev_i32_e32 v115, 31, v114
	v_lshl_add_u64 v[114:115], v[114:115], 2, s[42:43]
	s_lshl_b64 s[42:43], s[82:83], 2
	s_add_u32 s42, s35, s42
	s_addc_u32 s43, s38, s43
	v_lshl_add_u64 v[118:119], v[160:161], 2, s[42:43]
	s_nop 0
	s_nop 0
	v_cndmask_b32_e32 v168, v204, v168, vcc
	v_lshlrev_b32_e32 v169, 2, v168
	v_xor_b32_e32 v168, 32, v204
	v_cmp_lt_i32_e32 vcc, v168, v170
	s_waitcnt vmcnt(2)
	v_pk_mul_f32 v[178:179], v[176:177], v[136:137] op_sel:[1,0]
	v_pk_mul_f32 v[144:145], v[178:179], v[144:145]
	v_pk_mul_f32 v[178:179], v[176:177], v[126:127] op_sel:[1,0]
	v_pk_mul_f32 v[140:141], v[178:179], v[140:141]
	v_max_f32_e32 v144, 0, v144
	v_max_f32_e32 v140, 0, v140
	v_max_f32_e32 v145, 0, v145
	v_max_f32_e32 v141, 0, v141
	v_pk_mul_f32 v[144:145], v[144:145], v[144:145]
	v_pk_mul_f32 v[140:141], v[140:141], v[140:141]
	v_max_f32_e32 v178, v144, v140
	v_max_f32_e32 v179, v145, v141
	v_max3_f32 v178, v178, 0, v179
	v_mul_f32_e32 v179, v177, v138
	v_mul_f32_e32 v180, v177, v139
	v_mul_f32_e32 v146, v179, v146
	v_mul_f32_e32 v179, v177, v128
	v_mul_f32_e32 v147, v180, v147
	v_mul_f32_e32 v180, v177, v129
	v_mul_f32_e32 v142, v179, v142
	v_mul_f32_e32 v143, v180, v143
	v_max_f32_e32 v146, 0, v146
	v_max_f32_e32 v142, 0, v142
	v_max_f32_e32 v147, 0, v147
	v_max_f32_e32 v143, 0, v143
	v_pk_mul_f32 v[146:147], v[146:147], v[146:147]
	v_pk_mul_f32 v[142:143], v[142:143], v[142:143]
	v_max_f32_e32 v179, v146, v142
	v_max_f32_e32 v180, v147, v143
	v_max3_f32 v178, v178, v179, v180
	s_waitcnt vmcnt(0)
	v_mov_b32_e32 v114, v186
	v_mov_b32_e32 v115, v187
	v_mov_b32_e32 v116, v188
	v_mov_b32_e32 v117, v189
	v_mov_b32_e32 v118, v190
	v_mov_b32_e32 v119, v191
	v_mov_b32_e32 v120, v192
	v_mov_b32_e32 v121, v193
	v_mul_f32_e32 v179, v177, v118
	v_mul_f32_e32 v180, v177, v119
	v_mul_f32_e32 v132, v179, v132
	v_mul_f32_e32 v179, v177, v114
	v_mul_f32_e32 v133, v180, v133
	v_mul_f32_e32 v180, v177, v115
	v_mul_f32_e32 v122, v179, v122
	v_mul_f32_e32 v123, v180, v123
	v_max_f32_e32 v132, 0, v132
	v_max_f32_e32 v122, 0, v122
	v_max_f32_e32 v133, 0, v133
	v_max_f32_e32 v123, 0, v123
	v_pk_mul_f32 v[132:133], v[132:133], v[132:133]
	v_pk_mul_f32 v[122:123], v[122:123], v[122:123]
	v_max_f32_e32 v179, v132, v122
	v_max_f32_e32 v180, v133, v123
	v_max3_f32 v178, v178, v179, v180
	v_mul_f32_e32 v179, v177, v120
	v_mul_f32_e32 v134, v179, v134
	v_mul_f32_e32 v179, v177, v116
	v_mul_f32_e32 v180, v177, v121
	v_mul_f32_e32 v177, v177, v117
	v_mul_f32_e32 v124, v179, v124
	v_mul_f32_e32 v135, v180, v135
	v_mul_f32_e32 v125, v177, v125
	v_max_f32_e32 v134, 0, v134
	v_max_f32_e32 v124, 0, v124
	v_max_f32_e32 v135, 0, v135
	v_max_f32_e32 v125, 0, v125
	v_pk_mul_f32 v[134:135], v[134:135], v[134:135]
	v_pk_mul_f32 v[124:125], v[124:125], v[124:125]
	v_max_f32_e32 v179, v134, v124
	v_max_f32_e32 v177, v135, v125
	v_max3_f32 v177, v178, v179, v177
	ds_bpermute_b32 v178, v169, v177
	v_cndmask_b32_e32 v168, v204, v168, vcc
	v_lshlrev_b32_e32 v170, 2, v168
	v_cmp_eq_u32_e32 vcc, 0, v166
	v_lshl_add_u32 v168, v130, 2, s85
	s_waitcnt lgkmcnt(0)
	v_max_f32_e32 v178, v178, v178
	v_max_f32_e32 v177, v177, v178
	ds_bpermute_b32 v178, v170, v177
	s_and_saveexec_b64 s[42:43], vcc
	s_cbranch_execz .LBB0_1341
	s_waitcnt lgkmcnt(0)
	v_max_f32_e32 v178, v178, v178
	v_max_f32_e32 v177, v177, v177
	v_max_f32_e32 v177, v177, v178
	ds_write_b32 v168, v177
.LBB0_1341:
	s_or_b64 exec, exec, s[42:43]
	v_mul_f32_e32 v176, 0x3c010204, v176
	v_mul_f32_e32 v177, v176, v136
	s_waitcnt lgkmcnt(0)
	v_mul_f32_e32 v178, v176, v137
	v_mul_f32_e32 v110, v177, v110
	v_mul_f32_e32 v177, v176, v126
	v_mul_f32_e32 v111, v178, v111
	v_mul_f32_e32 v178, v176, v127
	v_mul_f32_e32 v106, v177, v106
	v_mul_f32_e32 v107, v178, v107
	v_max_f32_e32 v110, 0, v110
	v_max_f32_e32 v106, 0, v106
	v_max_f32_e32 v111, 0, v111
	v_max_f32_e32 v107, 0, v107
	v_pk_mul_f32 v[110:111], v[110:111], v[110:111]
	v_pk_mul_f32 v[106:107], v[106:107], v[106:107]
	v_max_f32_e32 v177, v110, v106
	v_max_f32_e32 v178, v111, v107
	v_max3_f32 v177, v177, 0, v178
	v_pk_mul_f32 v[178:179], v[176:177], v[138:139] op_sel_hi:[0,1]
	v_pk_mul_f32 v[112:113], v[178:179], v[112:113]
	v_pk_mul_f32 v[178:179], v[176:177], v[128:129] op_sel_hi:[0,1]
	v_pk_mul_f32 v[108:109], v[178:179], v[108:109]
	v_max_f32_e32 v112, 0, v112
	v_max_f32_e32 v108, 0, v108
	v_max_f32_e32 v113, 0, v113
	v_max_f32_e32 v109, 0, v109
	v_pk_mul_f32 v[112:113], v[112:113], v[112:113]
	v_pk_mul_f32 v[108:109], v[108:109], v[108:109]
	v_max_f32_e32 v178, v112, v108
	v_max_f32_e32 v179, v113, v109
	v_max3_f32 v177, v177, v178, v179
	v_pk_mul_f32 v[178:179], v[176:177], v[118:119] op_sel_hi:[0,1]
	v_pk_mul_f32 v[102:103], v[178:179], v[102:103]
	v_pk_mul_f32 v[178:179], v[176:177], v[114:115] op_sel_hi:[0,1]
	v_pk_mul_f32 v[98:99], v[178:179], v[98:99]
	v_max_f32_e32 v102, 0, v102
	v_max_f32_e32 v98, 0, v98
	v_max_f32_e32 v103, 0, v103
	v_max_f32_e32 v99, 0, v99
	v_pk_mul_f32 v[102:103], v[102:103], v[102:103]
	v_pk_mul_f32 v[98:99], v[98:99], v[98:99]
	v_max_f32_e32 v178, v102, v98
	v_max_f32_e32 v179, v103, v99
	v_max3_f32 v177, v177, v178, v179
	v_pk_mul_f32 v[178:179], v[176:177], v[120:121] op_sel_hi:[0,1]
	v_pk_mul_f32 v[104:105], v[178:179], v[104:105]
	v_mul_f32_e32 v178, v176, v116
	v_mul_f32_e32 v176, v176, v117
	v_mul_f32_e32 v100, v178, v100
	v_mul_f32_e32 v101, v176, v101
	v_max_f32_e32 v104, 0, v104
	v_max_f32_e32 v100, 0, v100
	v_max_f32_e32 v105, 0, v105
	v_max_f32_e32 v101, 0, v101
	v_pk_mul_f32 v[104:105], v[104:105], v[104:105]
	v_pk_mul_f32 v[100:101], v[100:101], v[100:101]
	v_max_f32_e32 v178, v104, v100
	v_max_f32_e32 v176, v105, v101
	v_max3_f32 v176, v177, v178, v176
	ds_bpermute_b32 v177, v169, v176
	s_waitcnt lgkmcnt(0)
	v_max_f32_e32 v177, v177, v177
	v_max_f32_e32 v176, v176, v177
	ds_bpermute_b32 v177, v170, v176
	s_and_saveexec_b64 s[42:43], vcc
	s_cbranch_execz .LBB0_1343
	s_waitcnt lgkmcnt(0)
	v_max_f32_e32 v177, v177, v177
	v_max_f32_e32 v176, v176, v176
	v_max_f32_e32 v176, v176, v177
	ds_write_b32 v168, v176 offset:64
;     __device__ __forceinline__ void operator()(f32x4 (&acc)[2][2][4][2], const Unit& u, int wr, int wc, int fr_in, int fq_in, int wid, LAS unsigned char* lds) const {
;     ...
;         for (int ai = 0; ai < 2; ++ai)
; #pragma unroll
;             for (int m = 0; m < 4; ++m) {
;                 const float s = sv[ai * 4 + m];
;                 float mx = 0.f;
; #pragma unroll
;                 for (int bj = 0; bj < 2; ++bj) {
;                     const v4i_t i0 = __builtin_bit_cast(v4i_t, acc[ai][bj][m][0]), i1 = __builtin_bit_cast(v4i_t, acc[ai][bj][m][1]);
;                     const u32x4 c0_ = cv[bj * 2], c1_ = cv[bj * 2 + 1];
;                     f32x4 v0, v1;
; #pragma unroll
;                     for (int j = 0; j < 4; ++j) { const float a = fmaxf((float)i0[j] * (s * __uint_as_float(c0_[j])), 0.f), b = fmaxf((float)i1[j] * (s * __uint_as_float(c1_[j])), 0.f); v0[j] = a * a; v1[j] = b * b; mx = fmaxf(mx, fmaxf(v0[j], v1[j])); }
;                     acc[ai][bj][m][0] = v0; acc[ai][bj][m][1] = v1;
;                 }
;                 mx = fmaxf(mx, __shfl_xor(mx, 16)); mx = fmaxf(mx, __shfl_xor(mx, 32));
;                 if (fq == 0) lmx[wc * 256 + wr * 64 + ai * HALF + m * 16 + fr] = mx;
.LBB0_1343:
	s_or_b64 exec, exec, s[42:43]
	v_mul_f32_e32 v175, 0x3c010204, v175
	s_waitcnt lgkmcnt(0)
	v_pk_mul_f32 v[176:177], v[174:175], v[136:137] op_sel:[1,0]
	v_pk_mul_f32 v[94:95], v[176:177], v[94:95]
	v_pk_mul_f32 v[176:177], v[174:175], v[126:127] op_sel:[1,0]
	v_pk_mul_f32 v[90:91], v[176:177], v[90:91]
	v_max_f32_e32 v94, 0, v94
	v_max_f32_e32 v90, 0, v90
	v_max_f32_e32 v95, 0, v95
	v_max_f32_e32 v91, 0, v91
	v_pk_mul_f32 v[94:95], v[94:95], v[94:95]
	v_pk_mul_f32 v[90:91], v[90:91], v[90:91]
	v_max_f32_e32 v176, v94, v90
	v_max_f32_e32 v177, v95, v91
	v_max3_f32 v176, v176, 0, v177
	v_mul_f32_e32 v177, v175, v138
	v_mul_f32_e32 v178, v175, v139
	v_mul_f32_e32 v96, v177, v96
	v_mul_f32_e32 v177, v175, v128
	v_mul_f32_e32 v97, v178, v97
	v_mul_f32_e32 v178, v175, v129
	v_mul_f32_e32 v92, v177, v92
	v_mul_f32_e32 v93, v178, v93
	v_max_f32_e32 v96, 0, v96
	v_max_f32_e32 v92, 0, v92
	v_max_f32_e32 v97, 0, v97
	v_max_f32_e32 v93, 0, v93
	v_pk_mul_f32 v[96:97], v[96:97], v[96:97]
	v_pk_mul_f32 v[92:93], v[92:93], v[92:93]
	v_max_f32_e32 v177, v96, v92
	v_max_f32_e32 v178, v97, v93
	v_max3_f32 v176, v176, v177, v178
	v_mul_f32_e32 v177, v175, v118
	v_mul_f32_e32 v178, v175, v119
	v_mul_f32_e32 v86, v177, v86
	v_mul_f32_e32 v177, v175, v114
	v_mul_f32_e32 v87, v178, v87
	v_mul_f32_e32 v178, v175, v115
	v_mul_f32_e32 v82, v177, v82
	v_mul_f32_e32 v83, v178, v83
	v_max_f32_e32 v86, 0, v86
	v_max_f32_e32 v82, 0, v82
	v_max_f32_e32 v87, 0, v87
	v_max_f32_e32 v83, 0, v83
	v_pk_mul_f32 v[86:87], v[86:87], v[86:87]
	v_pk_mul_f32 v[82:83], v[82:83], v[82:83]
	v_max_f32_e32 v177, v86, v82
	v_max_f32_e32 v178, v87, v83
	v_max3_f32 v176, v176, v177, v178
	v_mul_f32_e32 v177, v175, v120
	v_mul_f32_e32 v88, v177, v88
	v_mul_f32_e32 v177, v175, v116
	v_mul_f32_e32 v178, v175, v121
	v_mul_f32_e32 v175, v175, v117
	v_mul_f32_e32 v84, v177, v84
	v_mul_f32_e32 v89, v178, v89
	v_mul_f32_e32 v85, v175, v85
	v_max_f32_e32 v88, 0, v88
	v_max_f32_e32 v84, 0, v84
	v_max_f32_e32 v89, 0, v89
	v_max_f32_e32 v85, 0, v85
	v_pk_mul_f32 v[88:89], v[88:89], v[88:89]
	v_pk_mul_f32 v[84:85], v[84:85], v[84:85]
	v_max_f32_e32 v177, v88, v84
	v_max_f32_e32 v175, v89, v85
	v_max3_f32 v175, v176, v177, v175
	ds_bpermute_b32 v176, v169, v175
	s_waitcnt lgkmcnt(0)
	v_max_f32_e32 v176, v176, v176
	v_max_f32_e32 v175, v175, v176
	ds_bpermute_b32 v176, v170, v175
	s_and_saveexec_b64 s[42:43], vcc
	v_readlane_b32 s94, v255, 38
	s_cbranch_execz .LBB0_1345
	s_waitcnt lgkmcnt(0)
	v_max_f32_e32 v176, v176, v176
	v_max_f32_e32 v175, v175, v175
	v_max_f32_e32 v175, v175, v176
	ds_write_b32 v168, v175 offset:128
.LBB0_1345:
	s_or_b64 exec, exec, s[42:43]
	v_mul_f32_e32 v174, 0x3c010204, v174
	v_mul_f32_e32 v175, v174, v136
	s_waitcnt lgkmcnt(0)
	v_mul_f32_e32 v176, v174, v137
	v_mul_f32_e32 v78, v175, v78
	v_mul_f32_e32 v175, v174, v126
	v_mul_f32_e32 v79, v176, v79
	v_mul_f32_e32 v176, v174, v127
	v_mul_f32_e32 v74, v175, v74
	v_mul_f32_e32 v75, v176, v75
	v_max_f32_e32 v78, 0, v78
	v_max_f32_e32 v74, 0, v74
	v_max_f32_e32 v79, 0, v79
	v_max_f32_e32 v75, 0, v75
	v_pk_mul_f32 v[78:79], v[78:79], v[78:79]
	v_pk_mul_f32 v[74:75], v[74:75], v[74:75]
	v_max_f32_e32 v175, v78, v74
	v_max_f32_e32 v176, v79, v75
	v_max3_f32 v175, v175, 0, v176
	v_pk_mul_f32 v[176:177], v[174:175], v[138:139] op_sel_hi:[0,1]
	v_pk_mul_f32 v[80:81], v[176:177], v[80:81]
	v_pk_mul_f32 v[176:177], v[174:175], v[128:129] op_sel_hi:[0,1]
	v_pk_mul_f32 v[76:77], v[176:177], v[76:77]
	v_max_f32_e32 v80, 0, v80
	v_max_f32_e32 v76, 0, v76
	v_max_f32_e32 v81, 0, v81
	v_max_f32_e32 v77, 0, v77
	v_pk_mul_f32 v[80:81], v[80:81], v[80:81]
	v_pk_mul_f32 v[76:77], v[76:77], v[76:77]
	v_max_f32_e32 v176, v80, v76
	v_max_f32_e32 v177, v81, v77
	v_max3_f32 v175, v175, v176, v177
	v_pk_mul_f32 v[176:177], v[174:175], v[118:119] op_sel_hi:[0,1]
	v_pk_mul_f32 v[70:71], v[176:177], v[70:71]
	v_pk_mul_f32 v[176:177], v[174:175], v[114:115] op_sel_hi:[0,1]
	v_pk_mul_f32 v[66:67], v[176:177], v[66:67]
	v_max_f32_e32 v70, 0, v70
	v_max_f32_e32 v66, 0, v66
	v_max_f32_e32 v71, 0, v71
	v_max_f32_e32 v67, 0, v67
	v_pk_mul_f32 v[70:71], v[70:71], v[70:71]
	v_pk_mul_f32 v[66:67], v[66:67], v[66:67]
	v_max_f32_e32 v176, v70, v66
	v_max_f32_e32 v177, v71, v67
	v_max3_f32 v175, v175, v176, v177
	v_pk_mul_f32 v[176:177], v[174:175], v[120:121] op_sel_hi:[0,1]
	v_pk_mul_f32 v[72:73], v[176:177], v[72:73]
	v_mul_f32_e32 v176, v174, v116
	v_mul_f32_e32 v174, v174, v117
	v_mul_f32_e32 v68, v176, v68
	v_mul_f32_e32 v69, v174, v69
	v_max_f32_e32 v72, 0, v72
	v_max_f32_e32 v68, 0, v68
	v_max_f32_e32 v73, 0, v73
	v_max_f32_e32 v69, 0, v69
	v_pk_mul_f32 v[72:73], v[72:73], v[72:73]
	v_pk_mul_f32 v[68:69], v[68:69], v[68:69]
	v_max_f32_e32 v176, v72, v68
	v_max_f32_e32 v174, v73, v69
	v_max3_f32 v174, v175, v176, v174
	ds_bpermute_b32 v175, v169, v174
	s_waitcnt lgkmcnt(0)
	v_max_f32_e32 v175, v175, v175
	v_max_f32_e32 v174, v174, v175
	ds_bpermute_b32 v175, v170, v174
	s_and_saveexec_b64 s[42:43], vcc
	s_cbranch_execz .LBB0_1347
	s_waitcnt lgkmcnt(0)
	v_max_f32_e32 v175, v175, v175
	v_max_f32_e32 v174, v174, v174
	v_max_f32_e32 v174, v174, v175
	ds_write_b32 v168, v174 offset:192
;     __device__ __forceinline__ void operator()(f32x4 (&acc)[2][2][4][2], const Unit& u, int wr, int wc, int fr_in, int fq_in, int wid, LAS unsigned char* lds) const {
;     ...
;         for (int ai = 0; ai < 2; ++ai)
; #pragma unroll
;             for (int m = 0; m < 4; ++m) {
;                 const float s = sv[ai * 4 + m];
;                 float mx = 0.f;
; #pragma unroll
;                 for (int bj = 0; bj < 2; ++bj) {
;                     const v4i_t i0 = __builtin_bit_cast(v4i_t, acc[ai][bj][m][0]), i1 = __builtin_bit_cast(v4i_t, acc[ai][bj][m][1]);
;                     const u32x4 c0_ = cv[bj * 2], c1_ = cv[bj * 2 + 1];
;                     f32x4 v0, v1;
; #pragma unroll
;                     for (int j = 0; j < 4; ++j) { const float a = fmaxf((float)i0[j] * (s * __uint_as_float(c0_[j])), 0.f), b = fmaxf((float)i1[j] * (s * __uint_as_float(c1_[j])), 0.f); v0[j] = a * a; v1[j] = b * b; mx = fmaxf(mx, fmaxf(v0[j], v1[j])); }
;                     acc[ai][bj][m][0] = v0; acc[ai][bj][m][1] = v1;
;                 }
;                 mx = fmaxf(mx, __shfl_xor(mx, 16)); mx = fmaxf(mx, __shfl_xor(mx, 32));
;                 if (fq == 0) lmx[wc * 256 + wr * 64 + ai * HALF + m * 16 + fr] = mx;
.LBB0_1347:
	s_or_b64 exec, exec, s[42:43]
	v_mul_f32_e32 v173, 0x3c010204, v173
	s_waitcnt lgkmcnt(0)
	v_pk_mul_f32 v[174:175], v[172:173], v[136:137] op_sel:[1,0]
	v_pk_mul_f32 v[62:63], v[174:175], v[62:63]
	v_pk_mul_f32 v[174:175], v[172:173], v[126:127] op_sel:[1,0]
	v_pk_mul_f32 v[58:59], v[174:175], v[58:59]
	v_max_f32_e32 v62, 0, v62
	v_max_f32_e32 v58, 0, v58
	v_max_f32_e32 v63, 0, v63
	v_max_f32_e32 v59, 0, v59
	v_pk_mul_f32 v[62:63], v[62:63], v[62:63]
	v_pk_mul_f32 v[58:59], v[58:59], v[58:59]
	v_max_f32_e32 v174, v62, v58
	v_max_f32_e32 v175, v63, v59
	v_max3_f32 v174, v174, 0, v175
	v_mul_f32_e32 v175, v173, v138
	v_mul_f32_e32 v176, v173, v139
	v_mul_f32_e32 v64, v175, v64
	v_mul_f32_e32 v175, v173, v128
	v_mul_f32_e32 v65, v176, v65
	v_mul_f32_e32 v176, v173, v129
	v_mul_f32_e32 v60, v175, v60
	v_mul_f32_e32 v61, v176, v61
	v_max_f32_e32 v64, 0, v64
	v_max_f32_e32 v60, 0, v60
	v_max_f32_e32 v65, 0, v65
	v_max_f32_e32 v61, 0, v61
	v_pk_mul_f32 v[64:65], v[64:65], v[64:65]
	v_pk_mul_f32 v[60:61], v[60:61], v[60:61]
	v_max_f32_e32 v175, v64, v60
	v_max_f32_e32 v176, v65, v61
	v_max3_f32 v174, v174, v175, v176
	v_mul_f32_e32 v175, v173, v118
	v_mul_f32_e32 v176, v173, v119
	v_mul_f32_e32 v54, v175, v54
	v_mul_f32_e32 v175, v173, v114
	v_mul_f32_e32 v55, v176, v55
	v_mul_f32_e32 v176, v173, v115
	v_mul_f32_e32 v50, v175, v50
	v_mul_f32_e32 v51, v176, v51
	v_max_f32_e32 v54, 0, v54
	v_max_f32_e32 v50, 0, v50
	v_max_f32_e32 v55, 0, v55
	v_max_f32_e32 v51, 0, v51
	v_pk_mul_f32 v[54:55], v[54:55], v[54:55]
	v_pk_mul_f32 v[50:51], v[50:51], v[50:51]
	v_max_f32_e32 v175, v54, v50
	v_max_f32_e32 v176, v55, v51
	v_max3_f32 v174, v174, v175, v176
	v_mul_f32_e32 v175, v173, v120
	v_mul_f32_e32 v56, v175, v56
	v_mul_f32_e32 v175, v173, v116
	v_mul_f32_e32 v176, v173, v121
	v_mul_f32_e32 v173, v173, v117
	v_mul_f32_e32 v52, v175, v52
	v_mul_f32_e32 v57, v176, v57
	v_mul_f32_e32 v53, v173, v53
	v_max_f32_e32 v56, 0, v56
	v_max_f32_e32 v52, 0, v52
	v_max_f32_e32 v57, 0, v57
	v_max_f32_e32 v53, 0, v53
	v_pk_mul_f32 v[56:57], v[56:57], v[56:57]
	v_pk_mul_f32 v[52:53], v[52:53], v[52:53]
	v_max_f32_e32 v175, v56, v52
	v_max_f32_e32 v173, v57, v53
	v_max3_f32 v173, v174, v175, v173
	ds_bpermute_b32 v174, v169, v173
	s_waitcnt lgkmcnt(0)
	v_max_f32_e32 v174, v174, v174
	v_max_f32_e32 v173, v173, v174
	ds_bpermute_b32 v174, v170, v173
	s_and_saveexec_b64 s[42:43], vcc
	s_cbranch_execz .LBB0_1349
	s_waitcnt lgkmcnt(0)
	v_max_f32_e32 v174, v174, v174
	v_max_f32_e32 v173, v173, v173
	v_max_f32_e32 v173, v173, v174
	ds_write_b32 v168, v173 offset:512
.LBB0_1349:
	s_or_b64 exec, exec, s[42:43]
	v_mul_f32_e32 v172, 0x3c010204, v172
	v_mul_f32_e32 v173, v172, v136
	s_waitcnt lgkmcnt(0)
	v_mul_f32_e32 v174, v172, v137
	v_mul_f32_e32 v46, v173, v46
	v_mul_f32_e32 v173, v172, v126
	v_mul_f32_e32 v47, v174, v47
	v_mul_f32_e32 v174, v172, v127
	v_mul_f32_e32 v42, v173, v42
	v_mul_f32_e32 v43, v174, v43
	v_max_f32_e32 v46, 0, v46
	v_max_f32_e32 v42, 0, v42
	v_max_f32_e32 v47, 0, v47
	v_max_f32_e32 v43, 0, v43
	v_pk_mul_f32 v[46:47], v[46:47], v[46:47]
	v_pk_mul_f32 v[42:43], v[42:43], v[42:43]
	v_max_f32_e32 v173, v46, v42
	v_max_f32_e32 v174, v47, v43
	v_max3_f32 v173, v173, 0, v174
	v_pk_mul_f32 v[174:175], v[172:173], v[138:139] op_sel_hi:[0,1]
	v_pk_mul_f32 v[48:49], v[174:175], v[48:49]
	v_pk_mul_f32 v[174:175], v[172:173], v[128:129] op_sel_hi:[0,1]
	v_pk_mul_f32 v[44:45], v[174:175], v[44:45]
	v_max_f32_e32 v48, 0, v48
	v_max_f32_e32 v44, 0, v44
	v_max_f32_e32 v49, 0, v49
	v_max_f32_e32 v45, 0, v45
	v_pk_mul_f32 v[48:49], v[48:49], v[48:49]
	v_pk_mul_f32 v[44:45], v[44:45], v[44:45]
	v_max_f32_e32 v174, v48, v44
	v_max_f32_e32 v175, v49, v45
	v_max3_f32 v173, v173, v174, v175
	v_pk_mul_f32 v[174:175], v[172:173], v[118:119] op_sel_hi:[0,1]
	v_pk_mul_f32 v[38:39], v[174:175], v[38:39]
	v_pk_mul_f32 v[174:175], v[172:173], v[114:115] op_sel_hi:[0,1]
	v_pk_mul_f32 v[34:35], v[174:175], v[34:35]
	v_max_f32_e32 v38, 0, v38
	v_max_f32_e32 v34, 0, v34
	v_max_f32_e32 v39, 0, v39
	v_max_f32_e32 v35, 0, v35
	v_pk_mul_f32 v[38:39], v[38:39], v[38:39]
	v_pk_mul_f32 v[34:35], v[34:35], v[34:35]
	v_max_f32_e32 v174, v38, v34
	v_max_f32_e32 v175, v39, v35
	v_max3_f32 v173, v173, v174, v175
	v_pk_mul_f32 v[174:175], v[172:173], v[120:121] op_sel_hi:[0,1]
	v_pk_mul_f32 v[40:41], v[174:175], v[40:41]
	v_mul_f32_e32 v174, v172, v116
	v_mul_f32_e32 v172, v172, v117
	v_mul_f32_e32 v36, v174, v36
	v_mul_f32_e32 v37, v172, v37
	v_max_f32_e32 v40, 0, v40
	v_max_f32_e32 v36, 0, v36
	v_max_f32_e32 v41, 0, v41
	v_max_f32_e32 v37, 0, v37
	v_mul_f32_e32 v40, v40, v40
	v_mul_f32_e32 v36, v36, v36
	v_mul_f32_e32 v172, v41, v41
	v_mul_f32_e32 v41, v37, v37
	v_max_f32_e32 v174, v40, v36
	v_max_f32_e32 v37, v172, v41
	v_max3_f32 v37, v173, v174, v37
	ds_bpermute_b32 v173, v169, v37
	s_waitcnt lgkmcnt(0)
	v_max_f32_e32 v173, v173, v173
	v_max_f32_e32 v37, v37, v173
	ds_bpermute_b32 v173, v170, v37
	s_and_saveexec_b64 s[42:43], vcc
	s_cbranch_execz .LBB0_1351
	s_waitcnt lgkmcnt(0)
	v_max_f32_e32 v173, v173, v173
	v_max_f32_e32 v37, v37, v37
	v_max_f32_e32 v37, v37, v173
	ds_write_b32 v168, v37 offset:576
;     __device__ __forceinline__ void operator()(f32x4 (&acc)[2][2][4][2], const Unit& u, int wr, int wc, int fr_in, int fq_in, int wid, LAS unsigned char* lds) const {
;     ...
;         for (int ai = 0; ai < 2; ++ai)
; #pragma unroll
;             for (int m = 0; m < 4; ++m) {
;                 const float s = sv[ai * 4 + m];
;                 float mx = 0.f;
; #pragma unroll
;                 for (int bj = 0; bj < 2; ++bj) {
;                     const v4i_t i0 = __builtin_bit_cast(v4i_t, acc[ai][bj][m][0]), i1 = __builtin_bit_cast(v4i_t, acc[ai][bj][m][1]);
;                     const u32x4 c0_ = cv[bj * 2], c1_ = cv[bj * 2 + 1];
;                     f32x4 v0, v1;
; #pragma unroll
;                     for (int j = 0; j < 4; ++j) { const float a = fmaxf((float)i0[j] * (s * __uint_as_float(c0_[j])), 0.f), b = fmaxf((float)i1[j] * (s * __uint_as_float(c1_[j])), 0.f); v0[j] = a * a; v1[j] = b * b; mx = fmaxf(mx, fmaxf(v0[j], v1[j])); }
;                     acc[ai][bj][m][0] = v0; acc[ai][bj][m][1] = v1;
;                 }
;                 mx = fmaxf(mx, __shfl_xor(mx, 16)); mx = fmaxf(mx, __shfl_xor(mx, 32));
;                 if (fq == 0) lmx[wc * 256 + wr * 64 + ai * HALF + m * 16 + fr] = mx;
.LBB0_1351:
	s_or_b64 exec, exec, s[42:43]
	s_waitcnt lgkmcnt(0)
	v_mul_f32_e32 v173, 0x3c010204, v171
	v_mul_f32_e32 v37, v173, v136
	v_mul_f32_e32 v171, v173, v137
	v_mul_f32_e32 v30, v37, v30
	v_mul_f32_e32 v37, v173, v126
	v_mul_f32_e32 v31, v171, v31
	v_mul_f32_e32 v171, v173, v127
	v_mul_f32_e32 v26, v37, v26
	v_mul_f32_e32 v27, v171, v27
	v_max_f32_e32 v30, 0, v30
	v_max_f32_e32 v26, 0, v26
	v_max_f32_e32 v31, 0, v31
	v_max_f32_e32 v27, 0, v27
	v_pk_mul_f32 v[30:31], v[30:31], v[30:31]
	v_pk_mul_f32 v[26:27], v[26:27], v[26:27]
	v_max_f32_e32 v37, v30, v26
	v_max_f32_e32 v171, v31, v27
	v_max3_f32 v37, v37, 0, v171
	v_mul_f32_e32 v171, v173, v138
	v_mul_f32_e32 v174, v173, v139
	v_mul_f32_e32 v32, v171, v32
	v_mul_f32_e32 v171, v173, v128
	v_mul_f32_e32 v33, v174, v33
	v_mul_f32_e32 v174, v173, v129
	v_mul_f32_e32 v28, v171, v28
	v_mul_f32_e32 v29, v174, v29
	v_max_f32_e32 v32, 0, v32
	v_max_f32_e32 v28, 0, v28
	v_max_f32_e32 v33, 0, v33
	v_max_f32_e32 v29, 0, v29
	v_pk_mul_f32 v[32:33], v[32:33], v[32:33]
	v_pk_mul_f32 v[28:29], v[28:29], v[28:29]
	v_max_f32_e32 v171, v32, v28
	v_max_f32_e32 v174, v33, v29
	v_max3_f32 v174, v37, v171, v174
	v_mul_f32_e32 v37, v173, v118
	v_mul_f32_e32 v22, v37, v22
	v_mul_f32_e32 v37, v173, v114
	v_mul_f32_e32 v18, v37, v18
	v_max_f32_e32 v22, 0, v22
	v_max_f32_e32 v18, 0, v18
	v_mul_f32_e32 v37, v22, v22
	v_mul_f32_e32 v22, v18, v18
	v_cvt_f32_i32_e32 v18, v23
	v_mul_f32_e32 v23, v173, v119
	v_mul_f32_e32 v18, v23, v18
	v_mul_f32_e32 v23, v173, v115
	v_mul_f32_e32 v19, v23, v19
	v_max_f32_e32 v19, 0, v19
	v_mul_f32_e32 v23, v19, v19
	v_cvt_f32_i32_e32 v19, v24
	v_mul_f32_e32 v24, v173, v120
	v_max_f32_e32 v18, 0, v18
	v_mul_f32_e32 v19, v24, v19
	v_max_f32_e32 v19, 0, v19
	v_mul_f32_e32 v24, v173, v116
	v_mul_f32_e32 v20, v24, v20
	v_mul_f32_e32 v24, v19, v19
	v_cvt_f32_i32_e32 v19, v25
	v_mul_f32_e32 v171, v18, v18
	v_max_f32_e32 v175, v37, v22
	v_max_f32_e32 v18, v171, v23
	v_max3_f32 v18, v174, v175, v18
	v_mul_f32_e32 v174, v173, v121
	v_mul_f32_e32 v173, v173, v117
	v_mul_f32_e32 v19, v174, v19
	v_mul_f32_e32 v21, v173, v21
	v_max_f32_e32 v20, 0, v20
	v_max_f32_e32 v19, 0, v19
	v_max_f32_e32 v21, 0, v21
	v_mul_f32_e32 v20, v20, v20
	v_mul_f32_e32 v174, v19, v19
	v_mul_f32_e32 v173, v21, v21
	v_max_f32_e32 v25, v24, v20
	v_max_f32_e32 v19, v174, v173
	v_max3_f32 v18, v18, v25, v19
	ds_bpermute_b32 v19, v169, v18
	s_waitcnt lgkmcnt(0)
	v_max_f32_e32 v19, v19, v19
	v_max_f32_e32 v18, v18, v19
	ds_bpermute_b32 v19, v170, v18
	s_and_saveexec_b64 s[42:43], vcc
	s_cbranch_execz .LBB0_1353
	s_waitcnt lgkmcnt(0)
	v_max_f32_e32 v19, v19, v19
	v_max_f32_e32 v18, v18, v18
	v_max_f32_e32 v18, v18, v19
	ds_write_b32 v168, v18 offset:640
.LBB0_1353:
	s_or_b64 exec, exec, s[42:43]
	v_mul_f32_e32 v167, 0x3c010204, v167
	v_mul_f32_e32 v18, v167, v136
	v_mul_f32_e32 v14, v18, v14
	v_mul_f32_e32 v18, v167, v126
	v_mul_f32_e32 v10, v18, v10
	v_max_f32_e32 v14, 0, v14
	v_max_f32_e32 v10, 0, v10
	v_mul_f32_e32 v18, v14, v14
	v_mul_f32_e32 v14, v10, v10
	v_cvt_f32_i32_e32 v10, v15
	v_mul_f32_e32 v15, v167, v137
	v_mul_f32_e32 v10, v15, v10
	v_mul_f32_e32 v15, v167, v127
	v_mul_f32_e32 v11, v15, v11
	v_max_f32_e32 v11, 0, v11
	v_mul_f32_e32 v15, v11, v11
	v_cvt_f32_i32_e32 v11, v16
	v_mul_f32_e32 v16, v167, v138
	v_max_f32_e32 v10, 0, v10
	v_mul_f32_e32 v11, v16, v11
	v_max_f32_e32 v11, 0, v11
	v_mul_f32_e32 v16, v167, v128
	v_mul_f32_e32 v12, v16, v12
	v_mul_f32_e32 v16, v11, v11
	v_cvt_f32_i32_e32 v11, v17
	v_mul_f32_e32 v17, v167, v139
	s_waitcnt lgkmcnt(0)
	v_mul_f32_e32 v19, v10, v10
	v_max_f32_e32 v12, 0, v12
	v_mul_f32_e32 v11, v17, v11
	v_mul_f32_e32 v17, v167, v129
	v_mul_f32_e32 v13, v17, v13
	v_max_f32_e32 v11, 0, v11
	v_max_f32_e32 v13, 0, v13
	v_max_f32_e32 v21, v18, v14
	v_max_f32_e32 v10, v19, v15
	v_mul_f32_e32 v17, v11, v11
	v_pk_mul_f32 v[12:13], v[12:13], v[12:13]
	v_max3_f32 v10, v21, 0, v10
	v_max_f32_e32 v21, v16, v12
	v_max_f32_e32 v11, v17, v13
	v_max3_f32 v10, v10, v21, v11
	v_mul_f32_e32 v11, v167, v118
	v_mul_f32_e32 v6, v11, v6
	v_mul_f32_e32 v11, v167, v114
	v_mul_f32_e32 v2, v11, v2
	v_max_f32_e32 v2, 0, v2
	v_mul_f32_e32 v21, v2, v2
	v_cvt_f32_i32_e32 v2, v7
	v_mul_f32_e32 v7, v167, v119
	v_max_f32_e32 v6, 0, v6
	v_mul_f32_e32 v2, v7, v2
	v_mul_f32_e32 v7, v167, v115
	v_mul_f32_e32 v3, v7, v3
	v_max_f32_e32 v3, 0, v3
	v_max_f32_e32 v2, 0, v2
	v_pk_mul_f32 v[114:115], v[2:3], v[2:3] op_sel:[1,1] op_sel_hi:[0,0]
	v_cvt_f32_i32_e32 v3, v8
	v_mul_f32_e32 v25, v6, v6
	v_max_f32_e32 v6, v25, v21
	v_max_f32_e32 v2, v115, v114
	v_max3_f32 v2, v10, v6, v2
	v_mul_f32_e32 v6, v167, v120
	v_mul_f32_e32 v3, v6, v3
	v_max_f32_e32 v3, 0, v3
	v_mul_f32_e32 v118, v3, v3
	v_cvt_f32_i32_e32 v3, v9
	v_mul_f32_e32 v6, v167, v116
	v_mul_f32_e32 v4, v6, v4
	v_mul_f32_e32 v6, v167, v121
	v_mul_f32_e32 v3, v6, v3
	v_mul_f32_e32 v6, v167, v117
	v_mul_f32_e32 v5, v6, v5
	v_max_f32_e32 v4, 0, v4
	v_max_f32_e32 v3, 0, v3
	v_max_f32_e32 v5, 0, v5
	v_mul_f32_e32 v119, v3, v3
	v_pk_mul_f32 v[116:117], v[4:5], v[4:5]
	v_max_f32_e32 v4, v118, v116
	v_max_f32_e32 v3, v119, v117
	v_max3_f32 v2, v2, v4, v3
	ds_bpermute_b32 v3, v169, v2
	s_waitcnt lgkmcnt(0)
	v_max_f32_e32 v3, v3, v3
	v_max_f32_e32 v2, v2, v3
	ds_bpermute_b32 v3, v170, v2
	s_and_saveexec_b64 s[42:43], vcc
	s_cbranch_execz .LBB0_1355
	s_waitcnt lgkmcnt(0)
	v_max_f32_e32 v3, v3, v3
	v_max_f32_e32 v2, v2, v2
	v_max_f32_e32 v2, v2, v3
	ds_write_b32 v168, v2 offset:704

; #define LAS __attribute__((address_space(3)))
; #define LDS_WAIT() asm volatile("s_waitcnt lgkmcnt(0)" ::: "memory")
;     __device__ __forceinline__ void operator()(f32x4 (&acc)[2][2][4][2], const Unit& u, int wr, int wc, int fr_in, int fq_in, int wid, LAS unsigned char* lds) const {
;     ...
;         __builtin_amdgcn_s_barrier();
;         LAS float* lfin = lmx + 1024;
;         if (wid < 4) lfin[wid * 64 + lane] = __uint_as_float(__hip_atomic_load(rmax + u.pm * BM + wid * 64 + lane, __ATOMIC_RELAXED, __HIP_MEMORY_SCOPE_AGENT));
;         LDS_WAIT(); __builtin_amdgcn_s_barrier();
;         float rmv[8];
; #pragma unroll
;         for (int k = 0; k < 8; ++k) rmv[k] = lfin[wr * 64 + (k >> 2) * HALF + (k & 3) * 16 + fr];
;         unsigned char* H8 = UP8_H8;
; #pragma unroll
;         for (int ai = 0; ai < 2; ++ai)
; #pragma unroll
;             for (int m = 0; m < 4; ++m) {
;                 const float rm = rmv[ai * 4 + m], inv = rm > 0.f ? 255.0f * __builtin_amdgcn_rcpf(rm) : 0.f;
;                 u32x2 gb[2];
; #pragma unroll
;                 for (int bj = 0; bj < 2; ++bj) {
;                     const f32x4 v0 = acc[ai][bj][m][0], v1 = acc[ai][bj][m][1];
;                     unsigned w0 = 0u, w1 = 0u;
; #pragma unroll
;                     for (int j = 0; j < 4; ++j) { w0 = __builtin_amdgcn_cvt_pk_u8_f32(__builtin_rintf(v0[j] * inv), j, w0); w1 = __builtin_amdgcn_cvt_pk_u8_f32(__builtin_rintf(v1[j] * inv), j, w1); }
;                     gb[bj].x = w0 ^ 0x80808080u; gb[bj].y = w1 ^ 0x80808080u;
;                 }
;                 store_pair8(H8 + (size_t)(rowg + ai * HALF + m * 16) * DFF + colw, DFF, fr, fq, gb[0], gb[1]);
;             }
.LBB0_1377:
	s_add_u32 s40, s33, s82
	v_lshlrev_b32_e32 v4, 13, v130
	v_lshl_add_u32 v2, v130, 2, s22
	s_addc_u32 s41, s15, s83
	v_and_b32_e32 v8, 8, v130
	v_and_b32_e32 v130, 0xe000, v4
	s_waitcnt lgkmcnt(0)
	s_barrier
	ds_read2_b32 v[120:121], v2 offset1:16
	ds_read2_b32 v[10:11], v2 offset0:32 offset1:48
	ds_read2_b32 v[6:7], v2 offset0:128 offset1:144
	s_waitcnt vmcnt(0)
	ds_read2_b32 v[2:3], v2 offset0:160 offset1:176
	v_lshl_add_u64 v[4:5], s[40:41], 0, v[130:131]
	v_lshlrev_b32_e32 v130, 2, v8
	v_lshl_add_u64 v[4:5], v[4:5], 0, v[130:131]
	v_cmp_eq_u32_e32 vcc, 0, v8
	v_lshl_add_u64 v[8:9], v[4:5], 0, v[160:161]
	s_waitcnt lgkmcnt(3)
	v_rcp_f32_e32 v4, v120
	v_cmp_lt_f32_e64 s[52:53], 0, v120
	s_ashr_i32 s1, s0, 31
	s_lshl_b64 s[40:41], s[0:1], 13
	v_mul_f32_e32 v4, 0x437f0000, v4
	v_cndmask_b32_e64 v4, 0, v4, s[52:53]
	v_mul_f32_e32 v5, v144, v4
	v_rndne_f32_e32 v5, v5
	v_mul_f32_e32 v126, v145, v4
	v_cvt_pk_u8_f32 v5, v5, 0, 0
	v_mul_f32_e32 v120, v140, v4
	v_rndne_f32_e32 v126, v126
	v_rndne_f32_e32 v120, v120
	v_cvt_pk_u8_f32 v5, v126, 1, v5
	v_mul_f32_e32 v126, v141, v4
	v_cvt_pk_u8_f32 v120, v120, 0, 0
	v_rndne_f32_e32 v126, v126
	v_cvt_pk_u8_f32 v120, v126, 1, v120
	v_mul_f32_e32 v126, v146, v4
	v_rndne_f32_e32 v126, v126
	v_cvt_pk_u8_f32 v5, v126, 2, v5
	v_mul_f32_e32 v126, v142, v4
	v_rndne_f32_e32 v126, v126
	v_cvt_pk_u8_f32 v120, v126, 2, v120
	v_mul_f32_e32 v126, v147, v4
	v_rndne_f32_e32 v126, v126
	v_cvt_pk_u8_f32 v5, v126, 3, v5
	v_mul_f32_e32 v126, v143, v4
	v_pk_mul_f32 v[122:123], v[122:123], v[4:5] op_sel_hi:[1,0]
	v_rndne_f32_e32 v126, v126
	v_rndne_f32_e32 v122, v122
	v_cvt_pk_u8_f32 v120, v126, 3, v120
	v_pk_mul_f32 v[126:127], v[132:133], v[4:5] op_sel_hi:[1,0]
	v_cvt_pk_u8_f32 v122, v122, 0, 0
	v_rndne_f32_e32 v123, v123
	v_mul_f32_e32 v124, v124, v4
	v_rndne_f32_e32 v126, v126
	v_cvt_pk_u8_f32 v122, v123, 1, v122
	v_rndne_f32_e32 v124, v124
	v_cvt_pk_u8_f32 v126, v126, 0, 0
	v_rndne_f32_e32 v127, v127
	v_mul_f32_e32 v123, v134, v4
	v_cvt_pk_u8_f32 v122, v124, 2, v122
	v_mul_f32_e32 v124, v135, v4
	v_mul_f32_e32 v4, v125, v4
	v_cvt_pk_u8_f32 v126, v127, 1, v126
	v_rndne_f32_e32 v123, v123
	v_rndne_f32_e32 v4, v4
	v_cvt_pk_u8_f32 v123, v123, 2, v126
	v_rndne_f32_e32 v124, v124
	v_cvt_pk_u8_f32 v4, v4, 3, v122
	v_xor_b32_e32 v120, 0x80808080, v120
	v_cvt_pk_u8_f32 v123, v124, 3, v123
	v_xor_b32_e32 v4, 0x80808080, v4
	v_xor_b32_e32 v5, 0x80808080, v5
	v_xor_b32_e32 v124, 0x80808080, v123
	v_cndmask_b32_e32 v123, v120, v4, vcc
	v_mov_b32_e32 v126, v131
	v_cndmask_b32_e32 v122, v5, v124, vcc
	v_mov_b32_e32 v125, v131
	v_mov_b32_dpp v126, v123 row_ror:8 row_mask:0xf bank_mask:0xf
	v_cndmask_b32_e32 v123, v126, v120, vcc
	v_mov_b32_dpp v125, v122 row_ror:8 row_mask:0xf bank_mask:0xf
	v_rcp_f32_e32 v120, v121
	v_cndmask_b32_e32 v122, v125, v5, vcc
	v_cndmask_b32_e32 v124, v124, v125, vcc
	v_cndmask_b32_e32 v125, v4, v126, vcc
	v_lshl_add_u64 v[4:5], v[8:9], 0, s[40:41]
	s_mov_b32 s42, 0x10000
	global_store_dwordx2 v[4:5], v[122:123], off nt
	v_add_co_u32_e64 v122, s[52:53], s42, v4
	v_mul_f32_e32 v120, 0x437f0000, v120
	s_nop 0
	v_addc_co_u32_e64 v123, s[52:53], 0, v5, s[52:53]
	v_cmp_lt_f32_e64 s[52:53], 0, v121
	s_or_b32 s40, s0, 16
	s_ashr_i32 s41, s40, 31
	v_cndmask_b32_e64 v120, 0, v120, s[52:53]
	v_pk_mul_f32 v[106:107], v[106:107], v[120:121] op_sel_hi:[1,0]
	v_pk_mul_f32 v[98:99], v[98:99], v[120:121] op_sel_hi:[1,0]
	v_pk_mul_f32 v[110:111], v[110:111], v[120:121] op_sel_hi:[1,0]
	v_rndne_f32_e32 v106, v106
	v_pk_mul_f32 v[102:103], v[102:103], v[120:121] op_sel_hi:[1,0]
	v_rndne_f32_e32 v98, v98
	v_rndne_f32_e32 v110, v110
	v_cvt_pk_u8_f32 v106, v106, 0, 0
	v_rndne_f32_e32 v107, v107
	v_mul_f32_e32 v108, v108, v120
	v_rndne_f32_e32 v102, v102
	v_cvt_pk_u8_f32 v98, v98, 0, 0
	v_rndne_f32_e32 v99, v99
	v_mul_f32_e32 v100, v100, v120
	v_cvt_pk_u8_f32 v110, v110, 0, 0
	v_rndne_f32_e32 v111, v111
	v_cvt_pk_u8_f32 v106, v107, 1, v106
	v_mul_f32_e32 v107, v112, v120
	v_rndne_f32_e32 v108, v108
	v_cvt_pk_u8_f32 v102, v102, 0, 0
	v_rndne_f32_e32 v103, v103
	v_cvt_pk_u8_f32 v98, v99, 1, v98
	v_mul_f32_e32 v99, v104, v120
	v_rndne_f32_e32 v100, v100
	v_cvt_pk_u8_f32 v110, v111, 1, v110
	v_rndne_f32_e32 v107, v107
	v_cvt_pk_u8_f32 v106, v108, 2, v106
	v_mul_f32_e32 v108, v113, v120
	v_cvt_pk_u8_f32 v102, v103, 1, v102
	v_rndne_f32_e32 v99, v99
	v_cvt_pk_u8_f32 v98, v100, 2, v98
	v_mul_f32_e32 v100, v105, v120
	v_cvt_pk_u8_f32 v107, v107, 2, v110
	v_rndne_f32_e32 v108, v108
	v_cvt_pk_u8_f32 v99, v99, 2, v102
	v_rndne_f32_e32 v100, v100
	v_cvt_pk_u8_f32 v107, v108, 3, v107
	v_mul_f32_e32 v108, v109, v120
	v_cvt_pk_u8_f32 v99, v100, 3, v99
	v_mul_f32_e32 v100, v101, v120
	v_rndne_f32_e32 v108, v108
	v_rndne_f32_e32 v100, v100
	v_cvt_pk_u8_f32 v106, v108, 3, v106
	v_cvt_pk_u8_f32 v98, v100, 3, v98
	v_xor_b32_e32 v107, 0x80808080, v107
	v_xor_b32_e32 v106, 0x80808080, v106
	v_xor_b32_e32 v100, 0x80808080, v99
	v_xor_b32_e32 v101, 0x80808080, v98
	v_cndmask_b32_e32 v98, v107, v100, vcc
	v_cndmask_b32_e32 v99, v106, v101, vcc
	v_mov_b32_e32 v102, v131
	v_mov_b32_e32 v103, v131
	s_lshl_b64 s[40:41], s[40:41], 13
	v_mov_b32_dpp v102, v98 row_ror:8 row_mask:0xf bank_mask:0xf
	v_mov_b32_dpp v103, v99 row_ror:8 row_mask:0xf bank_mask:0xf
	v_cndmask_b32_e32 v98, v102, v107, vcc
	v_cndmask_b32_e32 v99, v103, v106, vcc
	v_cndmask_b32_e32 v100, v100, v102, vcc
	v_cndmask_b32_e32 v101, v101, v103, vcc
	v_lshl_add_u64 v[102:103], v[8:9], 0, s[40:41]
	global_store_dwordx2 v[102:103], v[98:99], off nt
	v_add_co_u32_e64 v98, s[52:53], s42, v102
	s_or_b32 s40, s0, 32
	s_nop 0
	v_addc_co_u32_e64 v99, s[52:53], 0, v103, s[52:53]
	s_waitcnt lgkmcnt(2)
;     __device__ __forceinline__ void operator()(f32x4 (&acc)[2][2][4][2], const Unit& u, int wr, int wc, int fr_in, int fq_in, int wid, LAS unsigned char* lds) const {
;     ...
;         for (int ai = 0; ai < 2; ++ai)
; #pragma unroll
;             for (int m = 0; m < 4; ++m) {
;                 const float rm = rmv[ai * 4 + m], inv = rm > 0.f ? 255.0f * __builtin_amdgcn_rcpf(rm) : 0.f;
;                 u32x2 gb[2];
; #pragma unroll
;                 for (int bj = 0; bj < 2; ++bj) {
;                     const f32x4 v0 = acc[ai][bj][m][0], v1 = acc[ai][bj][m][1];
;                     unsigned w0 = 0u, w1 = 0u;
; #pragma unroll
;                     for (int j = 0; j < 4; ++j) { w0 = __builtin_amdgcn_cvt_pk_u8_f32(__builtin_rintf(v0[j] * inv), j, w0); w1 = __builtin_amdgcn_cvt_pk_u8_f32(__builtin_rintf(v1[j] * inv), j, w1); }
;                     gb[bj].x = w0 ^ 0x80808080u; gb[bj].y = w1 ^ 0x80808080u;
;                 }
;                 store_pair8(H8 + (size_t)(rowg + ai * HALF + m * 16) * DFF + colw, DFF, fr, fq, gb[0], gb[1]);
;             }
	v_cmp_lt_f32_e64 s[52:53], 0, v10
	v_rcp_f32_e32 v10, v10
	s_ashr_i32 s41, s40, 31
	s_lshl_b64 s[40:41], s[40:41], 13
	s_or_b32 s0, s0, 48
	v_mul_f32_e32 v10, 0x437f0000, v10
	v_cndmask_b32_e64 v10, 0, v10, s[52:53]
	v_pk_mul_f32 v[90:91], v[90:91], v[10:11] op_sel_hi:[1,0]
	v_pk_mul_f32 v[94:95], v[94:95], v[10:11] op_sel_hi:[1,0]
	v_rndne_f32_e32 v90, v90
	v_rndne_f32_e32 v94, v94
	v_cvt_pk_u8_f32 v90, v90, 0, 0
	v_rndne_f32_e32 v91, v91
	v_mul_f32_e32 v92, v92, v10
	v_pk_mul_f32 v[82:83], v[82:83], v[10:11] op_sel_hi:[1,0]
	v_cvt_pk_u8_f32 v94, v94, 0, 0
	v_rndne_f32_e32 v95, v95
	v_cvt_pk_u8_f32 v90, v91, 1, v90
	v_mul_f32_e32 v91, v96, v10
	v_rndne_f32_e32 v92, v92
	v_pk_mul_f32 v[86:87], v[86:87], v[10:11] op_sel_hi:[1,0]
	v_rndne_f32_e32 v82, v82
	v_cvt_pk_u8_f32 v94, v95, 1, v94
	v_rndne_f32_e32 v91, v91
	v_cvt_pk_u8_f32 v90, v92, 2, v90
	v_mul_f32_e32 v92, v97, v10
	v_rndne_f32_e32 v86, v86
	v_cvt_pk_u8_f32 v82, v82, 0, 0
	v_rndne_f32_e32 v83, v83
	v_mul_f32_e32 v84, v84, v10
	v_cvt_pk_u8_f32 v91, v91, 2, v94
	v_rndne_f32_e32 v92, v92
	v_cvt_pk_u8_f32 v86, v86, 0, 0
	v_rndne_f32_e32 v87, v87
	v_cvt_pk_u8_f32 v82, v83, 1, v82
	v_mul_f32_e32 v83, v88, v10
	v_rndne_f32_e32 v84, v84
	v_cvt_pk_u8_f32 v91, v92, 3, v91
	v_mul_f32_e32 v92, v93, v10
	v_cvt_pk_u8_f32 v86, v87, 1, v86
	v_rndne_f32_e32 v83, v83
	v_cvt_pk_u8_f32 v82, v84, 2, v82
	v_mul_f32_e32 v84, v89, v10
	v_mul_f32_e32 v10, v85, v10
	v_rndne_f32_e32 v92, v92
	v_cvt_pk_u8_f32 v83, v83, 2, v86
	v_rndne_f32_e32 v84, v84
	v_rndne_f32_e32 v10, v10
	v_cvt_pk_u8_f32 v90, v92, 3, v90
	v_cvt_pk_u8_f32 v83, v84, 3, v83
	v_cvt_pk_u8_f32 v10, v10, 3, v82
	v_xor_b32_e32 v91, 0x80808080, v91
	v_xor_b32_e32 v90, 0x80808080, v90
	v_xor_b32_e32 v84, 0x80808080, v83
	v_xor_b32_e32 v10, 0x80808080, v10
	v_cndmask_b32_e32 v82, v91, v84, vcc
	v_cndmask_b32_e32 v83, v90, v10, vcc
	v_mov_b32_e32 v85, v131
	v_mov_b32_e32 v86, v131
	s_ashr_i32 s1, s0, 31
	v_mov_b32_dpp v85, v82 row_ror:8 row_mask:0xf bank_mask:0xf
	v_mov_b32_dpp v86, v83 row_ror:8 row_mask:0xf bank_mask:0xf
	v_cndmask_b32_e32 v82, v85, v91, vcc
	v_cndmask_b32_e32 v84, v84, v85, vcc
	v_cndmask_b32_e32 v85, v10, v86, vcc
	v_rcp_f32_e32 v10, v11
	v_cndmask_b32_e32 v83, v86, v90, vcc
	v_lshl_add_u64 v[86:87], v[8:9], 0, s[40:41]
	global_store_dwordx2 v[86:87], v[82:83], off nt
	v_add_co_u32_e64 v82, s[52:53], s42, v86
	v_mul_f32_e32 v10, 0x437f0000, v10
	s_nop 0
	v_addc_co_u32_e64 v83, s[52:53], 0, v87, s[52:53]
	v_cmp_lt_f32_e64 s[52:53], 0, v11
	s_lshl_b64 s[0:1], s[0:1], 13
	v_lshl_add_u64 v[8:9], v[8:9], 0, s[0:1]
	v_cndmask_b32_e64 v10, 0, v10, s[52:53]
	v_pk_mul_f32 v[74:75], v[74:75], v[10:11] op_sel_hi:[1,0]
	v_mul_f32_e32 v11, v78, v10
	v_rndne_f32_e32 v74, v74
	v_rndne_f32_e32 v11, v11
	v_cvt_pk_u8_f32 v74, v74, 0, 0
	v_mul_f32_e32 v78, v79, v10
	v_rndne_f32_e32 v75, v75
	v_cvt_pk_u8_f32 v11, v11, 0, 0
	v_rndne_f32_e32 v78, v78
	v_cvt_pk_u8_f32 v74, v75, 1, v74
	v_mul_f32_e32 v75, v80, v10
	v_cvt_pk_u8_f32 v11, v78, 1, v11
	v_rndne_f32_e32 v75, v75
	v_cvt_pk_u8_f32 v11, v75, 2, v11
	v_mul_f32_e32 v75, v76, v10
	v_pk_mul_f32 v[66:67], v[66:67], v[10:11] op_sel_hi:[1,0]
	v_rndne_f32_e32 v75, v75
	v_pk_mul_f32 v[70:71], v[70:71], v[10:11] op_sel_hi:[1,0]
	v_rndne_f32_e32 v66, v66
	v_cvt_pk_u8_f32 v74, v75, 2, v74
	v_mul_f32_e32 v75, v81, v10
	v_rndne_f32_e32 v70, v70
	v_cvt_pk_u8_f32 v66, v66, 0, 0
	v_rndne_f32_e32 v67, v67
	v_mul_f32_e32 v68, v68, v10
	v_rndne_f32_e32 v75, v75
	v_cvt_pk_u8_f32 v70, v70, 0, 0
	v_rndne_f32_e32 v71, v71
	v_cvt_pk_u8_f32 v66, v67, 1, v66
	v_mul_f32_e32 v67, v72, v10
	v_rndne_f32_e32 v68, v68
	v_cvt_pk_u8_f32 v11, v75, 3, v11
	v_mul_f32_e32 v75, v77, v10
	v_cvt_pk_u8_f32 v70, v71, 1, v70
	v_rndne_f32_e32 v67, v67
	v_cvt_pk_u8_f32 v66, v68, 2, v66
	v_mul_f32_e32 v68, v73, v10
	v_mul_f32_e32 v10, v69, v10
	v_rndne_f32_e32 v75, v75
	v_cvt_pk_u8_f32 v67, v67, 2, v70
	v_rndne_f32_e32 v68, v68
	v_rndne_f32_e32 v10, v10
	v_cvt_pk_u8_f32 v74, v75, 3, v74
	v_cvt_pk_u8_f32 v67, v68, 3, v67
	v_cvt_pk_u8_f32 v10, v10, 3, v66
	v_xor_b32_e32 v11, 0x80808080, v11
	v_xor_b32_e32 v74, 0x80808080, v74
	v_xor_b32_e32 v66, 0x80808080, v67
	v_xor_b32_e32 v67, 0x80808080, v10
	v_cndmask_b32_e32 v10, v11, v66, vcc
	v_cndmask_b32_e32 v68, v74, v67, vcc
	v_mov_b32_e32 v69, v131
	v_mov_b32_e32 v70, v131
	s_mov_b32 s0, 0x100000
	v_mov_b32_dpp v69, v10 row_ror:8 row_mask:0xf bank_mask:0xf
	v_mov_b32_dpp v70, v68 row_ror:8 row_mask:0xf bank_mask:0xf
	v_cndmask_b32_e32 v10, v69, v11, vcc
	v_cndmask_b32_e32 v11, v70, v74, vcc
	global_store_dwordx2 v[8:9], v[10:11], off nt
	v_add_co_u32_e64 v8, s[52:53], s42, v8
	v_cndmask_b32_e32 v66, v66, v69, vcc
	s_nop 0
	v_addc_co_u32_e64 v9, s[52:53], 0, v9, s[52:53]
	s_waitcnt lgkmcnt(1)
;     __device__ __forceinline__ void operator()(f32x4 (&acc)[2][2][4][2], const Unit& u, int wr, int wc, int fr_in, int fq_in, int wid, LAS unsigned char* lds) const {
;     ...
;         for (int ai = 0; ai < 2; ++ai)
; #pragma unroll
;             for (int m = 0; m < 4; ++m) {
;                 const float rm = rmv[ai * 4 + m], inv = rm > 0.f ? 255.0f * __builtin_amdgcn_rcpf(rm) : 0.f;
;                 u32x2 gb[2];
; #pragma unroll
;                 for (int bj = 0; bj < 2; ++bj) {
;                     const f32x4 v0 = acc[ai][bj][m][0], v1 = acc[ai][bj][m][1];
;                     unsigned w0 = 0u, w1 = 0u;
; #pragma unroll
;                     for (int j = 0; j < 4; ++j) { w0 = __builtin_amdgcn_cvt_pk_u8_f32(__builtin_rintf(v0[j] * inv), j, w0); w1 = __builtin_amdgcn_cvt_pk_u8_f32(__builtin_rintf(v1[j] * inv), j, w1); }
;                     gb[bj].x = w0 ^ 0x80808080u; gb[bj].y = w1 ^ 0x80808080u;
;                 }
;                 store_pair8(H8 + (size_t)(rowg + ai * HALF + m * 16) * DFF + colw, DFF, fr, fq, gb[0], gb[1]);
;             }
	v_cmp_lt_f32_e64 s[52:53], 0, v6
	v_rcp_f32_e32 v6, v6
	v_cndmask_b32_e32 v67, v67, v70, vcc
	global_store_dwordx2 v[8:9], v[66:67], off nt
	global_store_dwordx2 v[122:123], v[124:125], off nt
	v_mul_f32_e32 v6, 0x437f0000, v6
	v_cndmask_b32_e64 v6, 0, v6, s[52:53]
	v_mul_f32_e32 v8, v62, v6
	v_rndne_f32_e32 v8, v8
	v_mul_f32_e32 v10, v63, v6
	v_cvt_pk_u8_f32 v8, v8, 0, 0
	v_mul_f32_e32 v9, v58, v6
	v_rndne_f32_e32 v10, v10
	v_rndne_f32_e32 v9, v9
	v_cvt_pk_u8_f32 v8, v10, 1, v8
	v_mul_f32_e32 v10, v59, v6
	v_cvt_pk_u8_f32 v9, v9, 0, 0
	v_rndne_f32_e32 v10, v10
	v_cvt_pk_u8_f32 v9, v10, 1, v9
	v_mul_f32_e32 v10, v64, v6
	v_rndne_f32_e32 v10, v10
	v_cvt_pk_u8_f32 v8, v10, 2, v8
	v_mul_f32_e32 v10, v60, v6
	v_rndne_f32_e32 v10, v10
	v_cvt_pk_u8_f32 v9, v10, 2, v9
	v_mul_f32_e32 v10, v65, v6
	v_rndne_f32_e32 v10, v10
	v_cvt_pk_u8_f32 v8, v10, 3, v8
	v_mul_f32_e32 v10, v61, v6
	v_rndne_f32_e32 v10, v10
	v_cvt_pk_u8_f32 v9, v10, 3, v9
	v_mul_f32_e32 v10, v54, v6
	v_rndne_f32_e32 v10, v10
	v_mul_f32_e32 v11, v50, v6
	v_mul_f32_e32 v50, v55, v6
	v_cvt_pk_u8_f32 v10, v10, 0, 0
	v_rndne_f32_e32 v50, v50
	v_rndne_f32_e32 v11, v11
	v_cvt_pk_u8_f32 v10, v50, 1, v10
	v_mul_f32_e32 v50, v51, v6
	v_cvt_pk_u8_f32 v11, v11, 0, 0
	v_rndne_f32_e32 v50, v50
	v_cvt_pk_u8_f32 v11, v50, 1, v11
	v_mul_f32_e32 v50, v56, v6
	v_rndne_f32_e32 v50, v50
	v_cvt_pk_u8_f32 v10, v50, 2, v10
	v_mul_f32_e32 v50, v52, v6
	v_rndne_f32_e32 v50, v50
	v_cvt_pk_u8_f32 v11, v50, 2, v11
	v_mul_f32_e32 v50, v57, v6
	v_rndne_f32_e32 v50, v50
	v_mul_f32_e32 v6, v53, v6
	v_cvt_pk_u8_f32 v10, v50, 3, v10
	v_rndne_f32_e32 v6, v6
	v_xor_b32_e32 v8, 0x80808080, v8
	v_cvt_pk_u8_f32 v6, v6, 3, v11
	v_xor_b32_e32 v10, 0x80808080, v10
	v_xor_b32_e32 v9, 0x80808080, v9
	v_xor_b32_e32 v6, 0x80808080, v6
	v_cndmask_b32_e32 v11, v8, v10, vcc
	v_mov_b32_e32 v51, v131
	v_cndmask_b32_e32 v50, v9, v6, vcc
	global_store_dwordx2 v[98:99], v[100:101], off nt
	v_mov_b32_dpp v51, v11 row_ror:8 row_mask:0xf bank_mask:0xf
	v_mov_b32_e32 v11, v131
	v_cndmask_b32_e32 v8, v51, v8, vcc
	v_cndmask_b32_e32 v10, v10, v51, vcc
	v_mov_b32_dpp v11, v50 row_ror:8 row_mask:0xf bank_mask:0xf
	v_cndmask_b32_e32 v9, v11, v9, vcc
	v_cndmask_b32_e32 v11, v6, v11, vcc
	v_add_co_u32_e64 v50, s[52:53], s0, v4
	v_rcp_f32_e32 v6, v7
	s_nop 0
	v_addc_co_u32_e64 v51, s[52:53], 0, v5, s[52:53]
	s_mov_b32 s0, 0x110000
	global_store_dwordx2 v[50:51], v[8:9], off nt
	v_add_co_u32_e64 v8, s[52:53], s0, v4
	v_mul_f32_e32 v6, 0x437f0000, v6
	s_nop 0
	v_addc_co_u32_e64 v9, s[52:53], 0, v5, s[52:53]
	v_cmp_lt_f32_e64 s[52:53], 0, v7
	global_store_dwordx2 v[8:9], v[10:11], off nt
	s_mov_b32 s0, 0x120000
	v_cndmask_b32_e64 v6, 0, v6, s[52:53]
	v_mul_f32_e32 v7, v46, v6
	v_rndne_f32_e32 v7, v7
	v_mul_f32_e32 v9, v47, v6
	v_cvt_pk_u8_f32 v7, v7, 0, 0
	v_mul_f32_e32 v8, v42, v6
	v_rndne_f32_e32 v9, v9
	v_rndne_f32_e32 v8, v8
	v_cvt_pk_u8_f32 v7, v9, 1, v7
	v_mul_f32_e32 v9, v43, v6
	v_cvt_pk_u8_f32 v8, v8, 0, 0
	v_rndne_f32_e32 v9, v9
	v_cvt_pk_u8_f32 v8, v9, 1, v8
	v_mul_f32_e32 v9, v48, v6
	v_rndne_f32_e32 v9, v9
	v_cvt_pk_u8_f32 v7, v9, 2, v7
	v_mul_f32_e32 v9, v44, v6
	v_rndne_f32_e32 v9, v9
	v_cvt_pk_u8_f32 v8, v9, 2, v8
	v_mul_f32_e32 v9, v49, v6
	v_rndne_f32_e32 v9, v9
	v_cvt_pk_u8_f32 v7, v9, 3, v7
	v_mul_f32_e32 v9, v45, v6
	v_rndne_f32_e32 v9, v9
	v_cvt_pk_u8_f32 v8, v9, 3, v8
	v_mul_f32_e32 v9, v38, v6
	v_rndne_f32_e32 v9, v9
	v_mul_f32_e32 v11, v39, v6
	v_cvt_pk_u8_f32 v9, v9, 0, 0
	v_mul_f32_e32 v10, v34, v6
	v_rndne_f32_e32 v11, v11
	v_rndne_f32_e32 v10, v10
	v_cvt_pk_u8_f32 v9, v11, 1, v9
	v_mul_f32_e32 v11, v35, v6
	v_cvt_pk_u8_f32 v10, v10, 0, 0
	v_rndne_f32_e32 v11, v11
	v_cvt_pk_u8_f32 v10, v11, 1, v10
	v_mul_f32_e32 v11, v40, v6
	v_rndne_f32_e32 v11, v11
	v_cvt_pk_u8_f32 v9, v11, 2, v9
	v_mul_f32_e32 v11, v36, v6
	v_rndne_f32_e32 v11, v11
	v_cvt_pk_u8_f32 v10, v11, 2, v10
	v_mul_f32_e32 v11, v172, v6
	v_mul_f32_e32 v6, v41, v6
	v_rndne_f32_e32 v11, v11
	v_rndne_f32_e32 v6, v6
	v_cvt_pk_u8_f32 v9, v11, 3, v9
	v_cvt_pk_u8_f32 v6, v6, 3, v10
	v_xor_b32_e32 v7, 0x80808080, v7
	v_xor_b32_e32 v8, 0x80808080, v8
	v_xor_b32_e32 v9, 0x80808080, v9
	v_xor_b32_e32 v10, 0x80808080, v6
	v_cndmask_b32_e32 v6, v7, v9, vcc
	v_cndmask_b32_e32 v11, v8, v10, vcc
	v_mov_b32_e32 v34, v131
	v_mov_b32_e32 v35, v131
	global_store_dwordx2 v[82:83], v[84:85], off nt
	v_mov_b32_dpp v34, v6 row_ror:8 row_mask:0xf bank_mask:0xf
	v_mov_b32_dpp v35, v11 row_ror:8 row_mask:0xf bank_mask:0xf
	v_cndmask_b32_e32 v6, v34, v7, vcc
	v_cndmask_b32_e32 v7, v35, v8, vcc
	v_cndmask_b32_e32 v8, v9, v34, vcc
	v_cndmask_b32_e32 v9, v10, v35, vcc
	v_add_co_u32_e64 v10, s[52:53], s0, v4
	s_mov_b32 s0, 0x130000
	s_nop 0
	v_addc_co_u32_e64 v11, s[52:53], 0, v5, s[52:53]
	global_store_dwordx2 v[10:11], v[6:7], off nt
	v_add_co_u32_e64 v6, s[52:53], s0, v4
	v_mov_b32_e32 v11, v131
	s_nop 0
	v_addc_co_u32_e64 v7, s[52:53], 0, v5, s[52:53]
	s_waitcnt lgkmcnt(0)
; #define PG8_BAR __builtin_amdgcn_s_barrier()
; template <class Epi, class Sched, bool I8 = false>
; __device__ __forceinline__ void gemm_phase(LAS unsigned char* lds, const Gemm g, const Sched& S, const Epi& E) {
;     ...
;         if (PG8_ALIGN) { if (wr == 0) PG8_BAR; }
;         { Unit eu = cur; eu.pm = __builtin_amdgcn_readfirstlane(eu.pm); eu.pn = __builtin_amdgcn_readfirstlane(eu.pn); eu.seg = __builtin_amdgcn_readfirstlane(eu.seg); eu.ks = __builtin_amdgcn_readfirstlane(eu.ks); asm volatile("" : "+s"(eu.pm), "+s"(eu.pn), "+s"(eu.seg), "+s"(eu.ks));
;           if constexpr (epi_wide<Epi>::value) E(acc, eu, wr, wc, fr, fq, wid, lds); else E(acc, eu, wr, wc, fr, fq); }
;         if (!has_next) break;
;         if (nxt.seg == 0 || nxt.ks >= 0) {
; #pragma unroll
;             for (int a = 0; a < 2; ++a)
; #pragma unroll
;                 for (int b = 0; b < 2; ++b)
; #pragma unroll
;                     for (int m = 0; m < 4; ++m)
; #pragma unroll
;                         for (int n = 0; n < 2; ++n) acc[a][b][m][n] = (f32x4){0.f, 0.f, 0.f, 0.f};
;         }
;         cur = nxt; cA = nA; cB = nB; ++ui;
;         if (PG8_ALIGN) { if (wr == 1) PG8_BAR; }
;     __device__ __forceinline__ void operator()(f32x4 (&acc)[2][2][4][2], const Unit& u, int wr, int wc, int fr_in, int fq_in, int wid, LAS unsigned char* lds) const {
;     ...
;         for (int ai = 0; ai < 2; ++ai)
; #pragma unroll
;             for (int m = 0; m < 4; ++m) {
;                 const float rm = rmv[ai * 4 + m], inv = rm > 0.f ? 255.0f * __builtin_amdgcn_rcpf(rm) : 0.f;
;                 u32x2 gb[2];
; #pragma unroll
;                 for (int bj = 0; bj < 2; ++bj) {
;                     const f32x4 v0 = acc[ai][bj][m][0], v1 = acc[ai][bj][m][1];
;                     unsigned w0 = 0u, w1 = 0u;
; #pragma unroll
;                     for (int j = 0; j < 4; ++j) { w0 = __builtin_amdgcn_cvt_pk_u8_f32(__builtin_rintf(v0[j] * inv), j, w0); w1 = __builtin_amdgcn_cvt_pk_u8_f32(__builtin_rintf(v1[j] * inv), j, w1); }
;                     gb[bj].x = w0 ^ 0x80808080u; gb[bj].y = w1 ^ 0x80808080u;
;                 }
;                 store_pair8(H8 + (size_t)(rowg + ai * HALF + m * 16) * DFF + colw, DFF, fr, fq, gb[0], gb[1]);
;             }
	v_cmp_lt_f32_e64 s[52:53], 0, v2
	v_rcp_f32_e32 v2, v2
	global_store_dwordx2 v[6:7], v[8:9], off nt
	s_mov_b32 s0, 0x140000
	v_mul_f32_e32 v2, 0x437f0000, v2
	v_cndmask_b32_e64 v2, 0, v2, s[52:53]
	v_mul_f32_e32 v6, v30, v2
	v_rndne_f32_e32 v6, v6
	v_mul_f32_e32 v8, v31, v2
	v_cvt_pk_u8_f32 v6, v6, 0, 0
	v_mul_f32_e32 v7, v26, v2
	v_rndne_f32_e32 v8, v8
	v_rndne_f32_e32 v7, v7
	v_cvt_pk_u8_f32 v6, v8, 1, v6
	v_mul_f32_e32 v8, v27, v2
	v_cvt_pk_u8_f32 v7, v7, 0, 0
	v_rndne_f32_e32 v8, v8
	v_cvt_pk_u8_f32 v7, v8, 1, v7
	v_mul_f32_e32 v8, v32, v2
	v_rndne_f32_e32 v8, v8
	v_cvt_pk_u8_f32 v6, v8, 2, v6
	v_mul_f32_e32 v8, v28, v2
	v_rndne_f32_e32 v8, v8
	v_cvt_pk_u8_f32 v7, v8, 2, v7
	v_mul_f32_e32 v8, v33, v2
	v_rndne_f32_e32 v8, v8
	v_cvt_pk_u8_f32 v6, v8, 3, v6
	v_mul_f32_e32 v8, v29, v2
	v_rndne_f32_e32 v8, v8
	v_cvt_pk_u8_f32 v7, v8, 3, v7
	v_mul_f32_e32 v8, v37, v2
	v_rndne_f32_e32 v8, v8
	v_mul_f32_e32 v10, v171, v2
	v_cvt_pk_u8_f32 v8, v8, 0, 0
	v_mul_f32_e32 v9, v22, v2
	v_rndne_f32_e32 v10, v10
	v_rndne_f32_e32 v9, v9
	v_cvt_pk_u8_f32 v8, v10, 1, v8
	v_mul_f32_e32 v10, v23, v2
	v_cvt_pk_u8_f32 v9, v9, 0, 0
	v_rndne_f32_e32 v10, v10
	v_cvt_pk_u8_f32 v9, v10, 1, v9
	v_mul_f32_e32 v10, v24, v2
	v_rndne_f32_e32 v10, v10
	v_cvt_pk_u8_f32 v8, v10, 2, v8
	v_mul_f32_e32 v10, v20, v2
	v_rndne_f32_e32 v10, v10
	v_cvt_pk_u8_f32 v9, v10, 2, v9
	v_mul_f32_e32 v10, v174, v2
	v_rndne_f32_e32 v10, v10
	v_mul_f32_e32 v2, v173, v2
	v_cvt_pk_u8_f32 v8, v10, 3, v8
	v_rndne_f32_e32 v2, v2
	v_xor_b32_e32 v6, 0x80808080, v6
	v_cvt_pk_u8_f32 v2, v2, 3, v9
	v_xor_b32_e32 v8, 0x80808080, v8
	v_xor_b32_e32 v7, 0x80808080, v7
	v_xor_b32_e32 v2, 0x80808080, v2
	v_cndmask_b32_e32 v9, v6, v8, vcc
	v_cndmask_b32_e32 v10, v7, v2, vcc
	s_nop 0
	v_mov_b32_dpp v11, v9 row_ror:8 row_mask:0xf bank_mask:0xf
	v_mov_b32_e32 v9, v131
	v_cndmask_b32_e32 v6, v11, v6, vcc
	v_cndmask_b32_e32 v8, v8, v11, vcc
	v_mov_b32_dpp v9, v10 row_ror:8 row_mask:0xf bank_mask:0xf
	v_cndmask_b32_e32 v7, v9, v7, vcc
	v_cndmask_b32_e32 v9, v2, v9, vcc
	v_add_co_u32_e64 v10, s[52:53], s0, v4
	v_rcp_f32_e32 v2, v3
	s_nop 0
	v_addc_co_u32_e64 v11, s[52:53], 0, v5, s[52:53]
	s_mov_b32 s0, 0x150000
	global_store_dwordx2 v[10:11], v[6:7], off nt
	v_add_co_u32_e64 v6, s[52:53], s0, v4
	v_mul_f32_e32 v2, 0x437f0000, v2
	s_nop 0
	v_addc_co_u32_e64 v7, s[52:53], 0, v5, s[52:53]
	v_cmp_lt_f32_e64 s[52:53], 0, v3
	global_store_dwordx2 v[6:7], v[8:9], off nt
	v_mov_b32_e32 v10, v131
	v_cndmask_b32_e64 v2, 0, v2, s[52:53]
	v_mul_f32_e32 v3, v18, v2
	v_rndne_f32_e32 v3, v3
	v_mul_f32_e32 v7, v19, v2
	v_cvt_pk_u8_f32 v3, v3, 0, 0
	v_mul_f32_e32 v6, v14, v2
	v_rndne_f32_e32 v7, v7
	v_rndne_f32_e32 v6, v6
	v_cvt_pk_u8_f32 v3, v7, 1, v3
	v_mul_f32_e32 v7, v15, v2
	v_cvt_pk_u8_f32 v6, v6, 0, 0
	v_rndne_f32_e32 v7, v7
	v_cvt_pk_u8_f32 v6, v7, 1, v6
	v_mul_f32_e32 v7, v16, v2
	v_rndne_f32_e32 v7, v7
	v_cvt_pk_u8_f32 v3, v7, 2, v3
	v_mul_f32_e32 v7, v12, v2
	v_rndne_f32_e32 v7, v7
	v_cvt_pk_u8_f32 v6, v7, 2, v6
	v_mul_f32_e32 v7, v17, v2
	v_rndne_f32_e32 v7, v7
	v_cvt_pk_u8_f32 v3, v7, 3, v3
	v_mul_f32_e32 v7, v13, v2
	v_rndne_f32_e32 v7, v7
	v_cvt_pk_u8_f32 v6, v7, 3, v6
	v_mul_f32_e32 v7, v25, v2
	v_rndne_f32_e32 v7, v7
	v_mul_f32_e32 v9, v115, v2
	v_cvt_pk_u8_f32 v7, v7, 0, 0
	v_mul_f32_e32 v8, v21, v2
	v_rndne_f32_e32 v9, v9
	v_rndne_f32_e32 v8, v8
	v_cvt_pk_u8_f32 v7, v9, 1, v7
	v_mul_f32_e32 v9, v114, v2
	v_cvt_pk_u8_f32 v8, v8, 0, 0
	v_rndne_f32_e32 v9, v9
	v_cvt_pk_u8_f32 v8, v9, 1, v8
	v_mul_f32_e32 v9, v118, v2
	v_rndne_f32_e32 v9, v9
	v_cvt_pk_u8_f32 v7, v9, 2, v7
	v_mul_f32_e32 v9, v116, v2
	v_rndne_f32_e32 v9, v9
	v_cvt_pk_u8_f32 v8, v9, 2, v8
	v_mul_f32_e32 v9, v119, v2
	v_mul_f32_e32 v2, v117, v2
	v_rndne_f32_e32 v9, v9
	v_rndne_f32_e32 v2, v2
	v_cvt_pk_u8_f32 v7, v9, 3, v7
	v_cvt_pk_u8_f32 v2, v2, 3, v8
	v_xor_b32_e32 v3, 0x80808080, v3
	v_xor_b32_e32 v6, 0x80808080, v6
	v_xor_b32_e32 v7, 0x80808080, v7
	v_xor_b32_e32 v8, 0x80808080, v2
	v_cndmask_b32_e32 v2, v3, v7, vcc
	v_cndmask_b32_e32 v9, v6, v8, vcc
	v_mov_b32_e32 v11, v131
	v_mov_b32_dpp v10, v2 row_ror:8 row_mask:0xf bank_mask:0xf
	v_cndmask_b32_e32 v2, v10, v3, vcc
	v_mov_b32_dpp v11, v9 row_ror:8 row_mask:0xf bank_mask:0xf
	v_cndmask_b32_e32 v3, v11, v6, vcc
	v_cndmask_b32_e32 v6, v7, v10, vcc
	v_cndmask_b32_e32 v7, v8, v11, vcc
	v_add_co_u32_e32 v8, vcc, 0x160000, v4
	s_mov_b64 s[0:1], -1
	s_nop 0
	v_addc_co_u32_e32 v9, vcc, 0, v5, vcc
	global_store_dwordx2 v[8:9], v[2:3], off nt
	v_add_co_u32_e32 v2, vcc, 0x170000, v4
	s_nop 1
	v_addc_co_u32_e32 v3, vcc, 0, v5, vcc
	s_andn2_b64 vcc, exec, s[36:37]
	global_store_dwordx2 v[2:3], v[6:7], off nt
	s_cbranch_vccnz .LBB0_1330
	s_andn2_b64 vcc, exec, s[4:5]
	s_cbranch_vccnz .LBB0_1329
	s_barrier
	s_branch .LBB0_1329
